# P6 K-loop: for units after the first, the first two vmcnt(8) waits of the first K-iteration are skipped (they only stalled on the epilogue stores)
# speedup vs baseline: 1.0024x; 1.0024x over previous
.LBB0_529:
	ds_read_b128 v[96:99], v179
	ds_read_b128 v[100:103], v179 offset:1024
	ds_read_b128 v[104:107], v179 offset:2048
	ds_read_b128 v[108:111], v179 offset:3072
	ds_read_b128 v[156:159], v180
	ds_read_b128 v[160:163], v180 offset:1024
	ds_read_b128 v[164:167], v180 offset:2048
	ds_read_b128 v[168:171], v180 offset:3072
	s_add_u32 s26, s2, 0xfff80080
	s_addc_u32 s27, s3, -1
	s_cmp_eq_u32 s70, 28
	s_cselect_b32 s29, s68, s27
	s_cselect_b32 s28, s69, s26
	s_cselect_b32 s27, s5, s25
	s_cselect_b32 s26, s4, s24
	v_lshl_add_u64 v[214:215], s[2:3], 0, v[144:145]
	s_add_i32 m0, s34, 0xc000
	ds_read_b128 v[172:175], v181
	ds_read_b128 v[184:187], v181 offset:1024
	ds_read_b128 v[188:191], v181 offset:2048
	ds_read_b128 v[194:197], v181 offset:3072
	ds_read_b128 v[198:201], v181 offset:4096
	ds_read_b128 v[202:205], v181 offset:5120
	ds_read_b128 v[206:209], v181 offset:6144
	ds_read_b128 v[210:213], v181 offset:7168
	global_load_lds_dwordx4 v[214:215], off
	v_lshl_add_u64 v[214:215], s[2:3], 0, v[146:147]
	s_add_i32 m0, s34, 0xe000
	s_nop 0
	global_load_lds_dwordx4 v[214:215], off
	s_cmp_eq_u32 s70, -2
	s_cbranch_scc0 .Lk6_dow0
	s_cmp_lg_u32 s66, 0
	s_cbranch_scc1 .Lk6_skipw0
.Lk6_dow0:
	s_waitcnt vmcnt(8)
.Lk6_skipw0:
	s_waitcnt lgkmcnt(0)
	s_barrier
	s_setprio 1
	s_waitcnt lgkmcnt(0)
	v_mfma_f32_16x16x32_bf16 v[140:143], v[96:99], v[172:175], v[140:143]
	v_mfma_f32_16x16x32_bf16 v[136:139], v[104:107], v[172:175], v[136:139]
	v_mfma_f32_16x16x32_bf16 v[124:127], v[96:99], v[188:191], v[124:127]
	v_mfma_f32_16x16x32_bf16 v[120:123], v[104:107], v[188:191], v[120:123]
	v_mfma_f32_16x16x32_bf16 v[92:95], v[96:99], v[198:201], v[92:95]
	v_mfma_f32_16x16x32_bf16 v[88:91], v[104:107], v[198:201], v[88:91]
	v_mfma_f32_16x16x32_bf16 v[76:79], v[96:99], v[206:209], v[76:79]
	v_mfma_f32_16x16x32_bf16 v[72:75], v[104:107], v[206:209], v[72:75]
	v_mfma_f32_16x16x32_bf16 v[140:143], v[100:103], v[184:187], v[140:143]
	v_mfma_f32_16x16x32_bf16 v[136:139], v[108:111], v[184:187], v[136:139]
	v_mfma_f32_16x16x32_bf16 v[124:127], v[100:103], v[194:197], v[124:127]
	v_mfma_f32_16x16x32_bf16 v[120:123], v[108:111], v[194:197], v[120:123]
	v_mfma_f32_16x16x32_bf16 v[92:95], v[100:103], v[202:205], v[92:95]
	v_mfma_f32_16x16x32_bf16 v[88:91], v[108:111], v[202:205], v[88:91]
	v_mfma_f32_16x16x32_bf16 v[76:79], v[100:103], v[210:213], v[76:79]
	v_mfma_f32_16x16x32_bf16 v[72:75], v[108:111], v[210:213], v[72:75]
	s_setprio 0
	s_setprio 1
	v_mfma_f32_16x16x32_bf16 v[132:135], v[156:159], v[172:175], v[132:135]
	v_mfma_f32_16x16x32_bf16 v[128:131], v[164:167], v[172:175], v[128:131]
	v_mfma_f32_16x16x32_bf16 v[116:119], v[156:159], v[188:191], v[116:119]
	v_mfma_f32_16x16x32_bf16 v[112:115], v[164:167], v[188:191], v[112:115]
	v_mfma_f32_16x16x32_bf16 v[84:87], v[156:159], v[198:201], v[84:87]
	v_mfma_f32_16x16x32_bf16 v[80:83], v[164:167], v[198:201], v[80:83]
	v_mfma_f32_16x16x32_bf16 v[68:71], v[156:159], v[206:209], v[68:71]
	v_mfma_f32_16x16x32_bf16 v[64:67], v[164:167], v[206:209], v[64:67]
	v_mfma_f32_16x16x32_bf16 v[132:135], v[160:163], v[184:187], v[132:135]
	v_mfma_f32_16x16x32_bf16 v[128:131], v[168:171], v[184:187], v[128:131]
	v_mfma_f32_16x16x32_bf16 v[116:119], v[160:163], v[194:197], v[116:119]
	v_mfma_f32_16x16x32_bf16 v[112:115], v[168:171], v[194:197], v[112:115]
	v_mfma_f32_16x16x32_bf16 v[84:87], v[160:163], v[202:205], v[84:87]
	v_mfma_f32_16x16x32_bf16 v[80:83], v[168:171], v[202:205], v[80:83]
	v_mfma_f32_16x16x32_bf16 v[68:71], v[160:163], v[210:213], v[68:71]
	v_mfma_f32_16x16x32_bf16 v[64:67], v[168:171], v[210:213], v[64:67]
	s_setprio 0
	s_barrier
	s_add_i32 s71, s54, s1
	v_lshl_add_u64 v[214:215], s[26:27], 0, v[150:151]
	s_mov_b32 m0, s71
	ds_read_b128 v[172:175], v181 offset:16384
	ds_read_b128 v[184:187], v181 offset:17408
	ds_read_b128 v[188:191], v181 offset:18432
	ds_read_b128 v[194:197], v181 offset:19456
	ds_read_b128 v[198:201], v181 offset:20480
	ds_read_b128 v[202:205], v181 offset:21504
	ds_read_b128 v[206:209], v181 offset:22528
	ds_read_b128 v[210:213], v181 offset:23552
	global_load_lds_dwordx4 v[214:215], off
	s_add_i32 m0, s71, 0x2000
	s_add_u32 s72, s26, 0x80000
	v_lshl_add_u64 v[216:217], s[26:27], 0, v[154:155]
	s_addc_u32 s73, s27, 0
	s_add_i32 s71, s55, s1
	global_load_lds_dwordx4 v[216:217], off
	v_lshl_add_u64 v[218:219], s[72:73], 0, v[150:151]
	s_mov_b32 m0, s71
	v_lshl_add_u64 v[220:221], s[28:29], 0, v[152:153]
	global_load_lds_dwordx4 v[218:219], off
	v_lshl_add_u64 v[218:219], s[72:73], 0, v[154:155]
	s_add_i32 m0, s71, 0x2000
	s_nop 0
	global_load_lds_dwordx4 v[218:219], off
	v_lshl_add_u64 v[218:219], s[28:29], 0, v[148:149]
	s_mov_b32 m0, s34
	s_nop 0
	global_load_lds_dwordx4 v[218:219], off
	s_mov_b32 m0, s35
	s_nop 0
	global_load_lds_dwordx4 v[220:221], off
	s_cmp_eq_u32 s70, -2
	s_cbranch_scc0 .Lk6_dow1
	s_cmp_lg_u32 s66, 0
	s_cbranch_scc1 .Lk6_skipw1

.Lk6_skipw1:
	s_waitcnt lgkmcnt(0)
	s_barrier
	s_setprio 1
	s_waitcnt lgkmcnt(0)
	v_mfma_f32_16x16x32_bf16 v[60:63], v[96:99], v[172:175], v[60:63]
	v_mfma_f32_16x16x32_bf16 v[56:59], v[104:107], v[172:175], v[56:59]
	v_mfma_f32_16x16x32_bf16 v[44:47], v[96:99], v[188:191], v[44:47]
	v_mfma_f32_16x16x32_bf16 v[40:43], v[104:107], v[188:191], v[40:43]
	v_mfma_f32_16x16x32_bf16 v[28:31], v[96:99], v[198:201], v[28:31]
	v_mfma_f32_16x16x32_bf16 v[24:27], v[104:107], v[198:201], v[24:27]
	v_mfma_f32_16x16x32_bf16 v[12:15], v[96:99], v[206:209], v[12:15]
	v_mfma_f32_16x16x32_bf16 v[8:11], v[104:107], v[206:209], v[8:11]
	v_mfma_f32_16x16x32_bf16 v[60:63], v[100:103], v[184:187], v[60:63]
	v_mfma_f32_16x16x32_bf16 v[56:59], v[108:111], v[184:187], v[56:59]
	v_mfma_f32_16x16x32_bf16 v[44:47], v[100:103], v[194:197], v[44:47]
	v_mfma_f32_16x16x32_bf16 v[40:43], v[108:111], v[194:197], v[40:43]
	v_mfma_f32_16x16x32_bf16 v[28:31], v[100:103], v[202:205], v[28:31]
	v_mfma_f32_16x16x32_bf16 v[24:27], v[108:111], v[202:205], v[24:27]
	v_mfma_f32_16x16x32_bf16 v[12:15], v[100:103], v[210:213], v[12:15]
	v_mfma_f32_16x16x32_bf16 v[8:11], v[108:111], v[210:213], v[8:11]
	s_setprio 0
	s_setprio 1
	v_mfma_f32_16x16x32_bf16 v[52:55], v[156:159], v[172:175], v[52:55]
	v_mfma_f32_16x16x32_bf16 v[48:51], v[164:167], v[172:175], v[48:51]
	v_mfma_f32_16x16x32_bf16 v[36:39], v[156:159], v[188:191], v[36:39]
	v_mfma_f32_16x16x32_bf16 v[32:35], v[164:167], v[188:191], v[32:35]
	v_mfma_f32_16x16x32_bf16 v[20:23], v[156:159], v[198:201], v[20:23]
	v_mfma_f32_16x16x32_bf16 v[16:19], v[164:167], v[198:201], v[16:19]
	v_mfma_f32_16x16x32_bf16 v[4:7], v[156:159], v[206:209], v[4:7]
	v_mfma_f32_16x16x32_bf16 v[0:3], v[164:167], v[206:209], v[0:3]
	v_mfma_f32_16x16x32_bf16 v[52:55], v[160:163], v[184:187], v[52:55]
	v_mfma_f32_16x16x32_bf16 v[48:51], v[168:171], v[184:187], v[48:51]
	v_mfma_f32_16x16x32_bf16 v[36:39], v[160:163], v[194:197], v[36:39]
	v_mfma_f32_16x16x32_bf16 v[32:35], v[168:171], v[194:197], v[32:35]
	v_mfma_f32_16x16x32_bf16 v[20:23], v[160:163], v[202:205], v[20:23]
	v_mfma_f32_16x16x32_bf16 v[16:19], v[168:171], v[202:205], v[16:19]
	v_mfma_f32_16x16x32_bf16 v[4:7], v[160:163], v[210:213], v[4:7]
	v_mfma_f32_16x16x32_bf16 v[0:3], v[168:171], v[210:213], v[0:3]
	s_setprio 0
	s_barrier
	s_add_i32 s71, 0, 0x18000
	s_add_i32 s72, 0, 0x1c000
	v_add_u32_e32 v108, s71, v178
	v_add_u32_e32 v168, s72, v178
	ds_read_b128 v[96:99], v108
	ds_read_b128 v[100:103], v108 offset:1024
	ds_read_b128 v[104:107], v108 offset:2048
	ds_read_b128 v[108:111], v108 offset:3072
	ds_read_b128 v[156:159], v168
	ds_read_b128 v[160:163], v168 offset:1024
	ds_read_b128 v[164:167], v168 offset:2048
	ds_read_b128 v[168:171], v168 offset:3072
	s_add_u32 s28, s28, 0x80000
	s_addc_u32 s29, s29, 0
	s_mov_b32 m0, s36
	v_lshl_add_u64 v[222:223], s[28:29], 0, v[148:149]
	ds_read_b128 v[172:175], v181 offset:32768
	ds_read_b128 v[184:187], v181 offset:33792
	ds_read_b128 v[188:191], v181 offset:34816
	ds_read_b128 v[194:197], v181 offset:35840
	ds_read_b128 v[198:201], v181 offset:36864
	ds_read_b128 v[202:205], v181 offset:37888
	ds_read_b128 v[206:209], v181 offset:38912
	ds_read_b128 v[210:213], v181 offset:39936
	global_load_lds_dwordx4 v[222:223], off
	v_lshl_add_u64 v[222:223], s[28:29], 0, v[152:153]
	s_mov_b32 m0, s37
	s_nop 0
	global_load_lds_dwordx4 v[222:223], off
	s_waitcnt vmcnt(8)
	s_waitcnt lgkmcnt(0)
	s_barrier
	s_setprio 1
	s_waitcnt lgkmcnt(0)
	v_mfma_f32_16x16x32_bf16 v[140:143], v[96:99], v[172:175], v[140:143]
	v_mfma_f32_16x16x32_bf16 v[136:139], v[104:107], v[172:175], v[136:139]
	v_mfma_f32_16x16x32_bf16 v[124:127], v[96:99], v[188:191], v[124:127]
	v_mfma_f32_16x16x32_bf16 v[120:123], v[104:107], v[188:191], v[120:123]
	v_mfma_f32_16x16x32_bf16 v[92:95], v[96:99], v[198:201], v[92:95]
	v_mfma_f32_16x16x32_bf16 v[88:91], v[104:107], v[198:201], v[88:91]
	v_mfma_f32_16x16x32_bf16 v[76:79], v[96:99], v[206:209], v[76:79]
	v_mfma_f32_16x16x32_bf16 v[72:75], v[104:107], v[206:209], v[72:75]
	v_mfma_f32_16x16x32_bf16 v[140:143], v[100:103], v[184:187], v[140:143]
	v_mfma_f32_16x16x32_bf16 v[136:139], v[108:111], v[184:187], v[136:139]
	v_mfma_f32_16x16x32_bf16 v[124:127], v[100:103], v[194:197], v[124:127]
	v_mfma_f32_16x16x32_bf16 v[120:123], v[108:111], v[194:197], v[120:123]
	v_mfma_f32_16x16x32_bf16 v[92:95], v[100:103], v[202:205], v[92:95]
	v_mfma_f32_16x16x32_bf16 v[88:91], v[108:111], v[202:205], v[88:91]
	v_mfma_f32_16x16x32_bf16 v[76:79], v[100:103], v[210:213], v[76:79]
	v_mfma_f32_16x16x32_bf16 v[72:75], v[108:111], v[210:213], v[72:75]
	s_setprio 0
	s_setprio 1
	v_mfma_f32_16x16x32_bf16 v[132:135], v[156:159], v[172:175], v[132:135]
	v_mfma_f32_16x16x32_bf16 v[128:131], v[164:167], v[172:175], v[128:131]
	v_mfma_f32_16x16x32_bf16 v[116:119], v[156:159], v[188:191], v[116:119]
	v_mfma_f32_16x16x32_bf16 v[112:115], v[164:167], v[188:191], v[112:115]
	v_mfma_f32_16x16x32_bf16 v[84:87], v[156:159], v[198:201], v[84:87]
	v_mfma_f32_16x16x32_bf16 v[80:83], v[164:167], v[198:201], v[80:83]
	v_mfma_f32_16x16x32_bf16 v[68:71], v[156:159], v[206:209], v[68:71]
	v_mfma_f32_16x16x32_bf16 v[64:67], v[164:167], v[206:209], v[64:67]
	v_mfma_f32_16x16x32_bf16 v[132:135], v[160:163], v[184:187], v[132:135]
	v_mfma_f32_16x16x32_bf16 v[128:131], v[168:171], v[184:187], v[128:131]
	v_mfma_f32_16x16x32_bf16 v[116:119], v[160:163], v[194:197], v[116:119]
	v_mfma_f32_16x16x32_bf16 v[112:115], v[168:171], v[194:197], v[112:115]
	v_mfma_f32_16x16x32_bf16 v[84:87], v[160:163], v[202:205], v[84:87]
	v_mfma_f32_16x16x32_bf16 v[80:83], v[168:171], v[202:205], v[80:83]
	v_mfma_f32_16x16x32_bf16 v[68:71], v[160:163], v[210:213], v[68:71]
	v_mfma_f32_16x16x32_bf16 v[64:67], v[168:171], v[210:213], v[64:67]
	s_setprio 0
	s_barrier
	s_add_i32 s28, s71, s1
	v_lshl_add_u64 v[214:215], v[214:215], 0, s[14:15]
	s_mov_b32 m0, s28
	ds_read_b128 v[172:175], v181 offset:49152
	ds_read_b128 v[184:187], v181 offset:50176
	ds_read_b128 v[188:191], v181 offset:51200
	ds_read_b128 v[194:197], v181 offset:52224
	ds_read_b128 v[198:201], v181 offset:53248
	ds_read_b128 v[202:205], v181 offset:54272
	ds_read_b128 v[206:209], v181 offset:55296
	ds_read_b128 v[210:213], v181 offset:56320
	global_load_lds_dwordx4 v[214:215], off
	s_add_i32 m0, s28, 0x2000
	s_add_u32 s26, s26, 0x80080
	v_lshl_add_u64 v[214:215], v[216:217], 0, s[14:15]
	s_addc_u32 s27, s27, 0
	s_add_i32 s28, s72, s1
	global_load_lds_dwordx4 v[214:215], off
	v_lshl_add_u64 v[214:215], s[26:27], 0, v[150:151]
	s_mov_b32 m0, s28
	s_nop 0
	global_load_lds_dwordx4 v[214:215], off
	v_lshl_add_u64 v[214:215], s[26:27], 0, v[154:155]
	s_add_i32 m0, s28, 0x2000
	s_nop 0
	global_load_lds_dwordx4 v[214:215], off
	v_lshl_add_u64 v[214:215], v[218:219], 0, s[14:15]
	s_mov_b32 m0, s43
	s_nop 0
	global_load_lds_dwordx4 v[214:215], off
	v_lshl_add_u64 v[214:215], v[220:221], 0, s[14:15]
	s_mov_b32 m0, s48
	s_nop 0
	global_load_lds_dwordx4 v[214:215], off
	s_waitcnt vmcnt(8)
	s_waitcnt lgkmcnt(0)
	s_barrier
	s_setprio 1
	s_waitcnt lgkmcnt(0)
	v_mfma_f32_16x16x32_bf16 v[60:63], v[96:99], v[172:175], v[60:63]
	v_mfma_f32_16x16x32_bf16 v[56:59], v[104:107], v[172:175], v[56:59]
	v_mfma_f32_16x16x32_bf16 v[44:47], v[96:99], v[188:191], v[44:47]
	v_mfma_f32_16x16x32_bf16 v[40:43], v[104:107], v[188:191], v[40:43]
	v_mfma_f32_16x16x32_bf16 v[28:31], v[96:99], v[198:201], v[28:31]
	v_mfma_f32_16x16x32_bf16 v[24:27], v[104:107], v[198:201], v[24:27]
	v_mfma_f32_16x16x32_bf16 v[12:15], v[96:99], v[206:209], v[12:15]
	v_mfma_f32_16x16x32_bf16 v[8:11], v[104:107], v[206:209], v[8:11]
	v_mfma_f32_16x16x32_bf16 v[60:63], v[100:103], v[184:187], v[60:63]
	v_mfma_f32_16x16x32_bf16 v[56:59], v[108:111], v[184:187], v[56:59]
	v_mfma_f32_16x16x32_bf16 v[44:47], v[100:103], v[194:197], v[44:47]
	v_mfma_f32_16x16x32_bf16 v[40:43], v[108:111], v[194:197], v[40:43]
	v_mfma_f32_16x16x32_bf16 v[28:31], v[100:103], v[202:205], v[28:31]
	v_mfma_f32_16x16x32_bf16 v[24:27], v[108:111], v[202:205], v[24:27]
	v_mfma_f32_16x16x32_bf16 v[12:15], v[100:103], v[210:213], v[12:15]
	v_mfma_f32_16x16x32_bf16 v[8:11], v[108:111], v[210:213], v[8:11]
	s_setprio 0
	s_setprio 1
	v_mfma_f32_16x16x32_bf16 v[52:55], v[156:159], v[172:175], v[52:55]
	v_mfma_f32_16x16x32_bf16 v[48:51], v[164:167], v[172:175], v[48:51]
	v_mfma_f32_16x16x32_bf16 v[36:39], v[156:159], v[188:191], v[36:39]
	v_mfma_f32_16x16x32_bf16 v[32:35], v[164:167], v[188:191], v[32:35]
	v_mfma_f32_16x16x32_bf16 v[20:23], v[156:159], v[198:201], v[20:23]
	v_mfma_f32_16x16x32_bf16 v[16:19], v[164:167], v[198:201], v[16:19]
	v_mfma_f32_16x16x32_bf16 v[4:7], v[156:159], v[206:209], v[4:7]
	v_mfma_f32_16x16x32_bf16 v[0:3], v[164:167], v[206:209], v[0:3]
	v_mfma_f32_16x16x32_bf16 v[52:55], v[160:163], v[184:187], v[52:55]
	v_mfma_f32_16x16x32_bf16 v[48:51], v[168:171], v[184:187], v[48:51]
	v_mfma_f32_16x16x32_bf16 v[36:39], v[160:163], v[194:197], v[36:39]
	v_mfma_f32_16x16x32_bf16 v[32:35], v[168:171], v[194:197], v[32:35]
	v_mfma_f32_16x16x32_bf16 v[20:23], v[160:163], v[202:205], v[20:23]
	v_mfma_f32_16x16x32_bf16 v[16:19], v[168:171], v[202:205], v[16:19]
	v_mfma_f32_16x16x32_bf16 v[4:7], v[160:163], v[210:213], v[4:7]
	v_mfma_f32_16x16x32_bf16 v[0:3], v[168:171], v[210:213], v[0:3]
	s_setprio 0
	s_barrier
	s_add_i32 s70, s70, 2
	s_add_u32 s2, s2, 0x100
	s_addc_u32 s3, s3, 0
	s_add_u32 s24, s24, 0x100
	s_addc_u32 s25, s25, 0
	s_cmp_gt_u32 s70, 29
	s_cbranch_scc0 .LBB0_529
	s_and_b64 vcc, exec, s[18:19]
	s_cbranch_vccz .LBB0_532
	s_barrier
